# v73 + same LDS cache of the per-row rstd values in the w_in (phase 3) epilogue: its 8 serialized load+wait+sqrt/div chains run only on the first tile
# speedup vs baseline: 1.0111x; 1.0111x over previous
.LBB0_306:
	s_mov_b32 s98, -1
	s_cmp_lt_i32 s58, 4
	s_cselect_b64 s[2:3], -1, 0
	s_and_b64 s[2:3], s[2:3], s[0:1]
	s_andn2_b64 vcc, exec, s[2:3]
	s_cbranch_vccnz .LBB0_434
	s_cmpk_lt_i32 s84, 0x980
	v_readfirstlane_b32 s6, v220
	s_movk_i32 s0, 0x800
	s_cselect_b64 s[4:5], -1, 0
	s_cmpk_gt_i32 s84, 0x97f
	s_cbranch_scc1 .LBB0_309
	s_ashr_i32 s1, s84, 31
	s_lshr_b32 s1, s1, 29
	s_add_i32 s1, s84, s1
	s_ashr_i32 s7, s1, 3
	s_and_b32 s1, s1, -8
	s_sub_i32 s1, s84, s1
	s_cmp_lt_i32 s1, 0
	s_movk_i32 s8, 0x131
	s_cselect_b32 s8, s8, 0x130
	s_mul_i32 s1, s1, s8
	s_add_i32 s1, s1, s7
	s_mul_hi_i32 s7, s1, 0x6bca1af3
	s_lshr_b32 s8, s7, 31
	s_ashr_i32 s7, s7, 7
	s_add_i32 s7, s7, s8
	s_lshl_b32 s8, s7, 3
	s_mulk_i32 s7, 0x130
	s_sub_i32 s1, s1, s7
	s_bfe_u32 s7, s1, 0x3001c
	s_add_i32 s7, s1, s7
	s_sext_i32_i16 s9, s7
	s_and_b32 s7, s7, 0xfff8
	s_sub_i32 s1, s1, s7
	s_sext_i32_i16 s1, s1
	s_add_i32 s12, s8, s1
	s_ashr_i32 s89, s9, 3

.LBB0_326:
	s_cmp_eq_u32 s12, s98
	s_cbranch_scc0 .Lrstd_miss_326
	v_lshl_add_u32 v210, s12, 8, v175
	v_ashrrev_i32_e32 v211, 31, v210
	v_or_b32_e32 v212, 16, v210
	v_ashrrev_i32_e32 v213, 31, v212
	v_or_b32_e32 v202, 32, v210
	v_ashrrev_i32_e32 v203, 31, v202
	v_or_b32_e32 v204, 48, v210
	v_ashrrev_i32_e32 v205, 31, v204
	v_add_u32_e32 v186, 0x80, v210
	v_add_u32_e32 v190, 0x90, v210
	v_add_u32_e32 v184, 0xa0, v210
	v_add_u32_e32 v188, 0xb0, v210
	v_ashrrev_i32_e32 v187, 31, v186
	v_ashrrev_i32_e32 v191, 31, v190
	v_ashrrev_i32_e32 v185, 31, v184
	v_ashrrev_i32_e32 v189, 31, v188
	v_and_b32_e32 v128, 15, v220
	v_lshrrev_b32_e32 v129, 6, v220
	v_lshlrev_b32_e32 v128, 5, v128
	v_lshl_add_u32 v128, v129, 9, v128
	v_add_u32_e32 v128, 0x20000, v128
	ds_read_b128 v[132:135], v128
	ds_read_b128 v[128:131], v128 offset:16
	s_cmp_gt_i32 s89, 4
	s_mov_b64 s[0:1], -1
	s_waitcnt lgkmcnt(0)
	v_mov_b32_e32 v206, v132
	v_mov_b32_e32 v208, v133
	v_mov_b32_e32 v198, v134
	v_mov_b32_e32 v200, v135
	v_mov_b32_e32 v194, v128
	v_mov_b32_e32 v196, v129
	v_mov_b32_e32 v192, v130
	v_mov_b32_e32 v214, v131
	s_branch .Lrstd_join_326
.Lrstd_miss_326:
	v_lshl_add_u32 v210, s12, 8, v175
	v_ashrrev_i32_e32 v211, 31, v210
	v_lshl_add_u64 v[128:129], v[210:211], 2, s[34:35]
	global_load_dword v130, v[128:129], off
	v_or_b32_e32 v212, 16, v210
	v_ashrrev_i32_e32 v213, 31, v212
	v_or_b32_e32 v202, 32, v210
	v_ashrrev_i32_e32 v203, 31, v202
	v_or_b32_e32 v204, 48, v210
	v_ashrrev_i32_e32 v205, 31, v204
	v_add_u32_e32 v186, 0x80, v210
	v_add_u32_e32 v190, 0x90, v210
	v_add_u32_e32 v184, 0xa0, v210
	v_add_u32_e32 v188, 0xb0, v210
	v_ashrrev_i32_e32 v187, 31, v186
	v_ashrrev_i32_e32 v191, 31, v190
	v_ashrrev_i32_e32 v185, 31, v184
	v_ashrrev_i32_e32 v189, 31, v188
	s_cmp_gt_i32 s89, 4
	s_waitcnt vmcnt(0)
	v_fmamk_f32 v130, v130, 0x3a000000, v225
	v_cmp_gt_f32_e32 vcc, s84, v130
	v_mul_f32_e32 v131, 0x4f800000, v130
	s_nop 0
	v_cndmask_b32_e32 v130, v130, v131, vcc
	v_sqrt_f32_e32 v131, v130
	s_nop 0
	v_add_u32_e32 v132, -1, v131
	v_fma_f32 v133, -v132, v131, v130
	v_cmp_ge_f32_e64 s[0:1], 0, v133
	v_add_u32_e32 v133, 1, v131
	s_nop 0
	v_cndmask_b32_e64 v132, v131, v132, s[0:1]
	v_fma_f32 v131, -v133, v131, v130
	v_cmp_lt_f32_e64 s[0:1], 0, v131
	s_nop 1
	v_cndmask_b32_e64 v131, v132, v133, s[0:1]
	v_mul_f32_e32 v132, 0x37800000, v131
	v_cndmask_b32_e32 v131, v131, v132, vcc
	v_cmp_class_f32_e32 vcc, v130, v226
	s_nop 1
	v_cndmask_b32_e32 v130, v131, v130, vcc
	v_div_scale_f32 v131, s[0:1], v130, v130, 1.0
	v_rcp_f32_e32 v132, v131
	s_nop 0
	v_fma_f32 v133, -v131, v132, 1.0
	v_fmac_f32_e32 v132, v133, v132
	v_div_scale_f32 v133, vcc, 1.0, v130, 1.0
	v_mul_f32_e32 v134, v133, v132
	v_fma_f32 v135, -v131, v134, v133
	v_fmac_f32_e32 v134, v135, v132
	v_fma_f32 v131, -v131, v134, v133
	v_div_fmas_f32 v131, v131, v132, v134
	v_div_fixup_f32 v206, v131, v130, 1.0
	v_lshl_add_u64 v[130:131], v[212:213], 2, s[34:35]
	global_load_dword v130, v[130:131], off
	s_waitcnt vmcnt(0)
	v_fmamk_f32 v130, v130, 0x3a000000, v225
	v_cmp_gt_f32_e32 vcc, s84, v130
	v_mul_f32_e32 v131, 0x4f800000, v130
	s_nop 0
	v_cndmask_b32_e32 v130, v130, v131, vcc
	v_sqrt_f32_e32 v131, v130
	s_nop 0
	v_add_u32_e32 v132, -1, v131
	v_fma_f32 v133, -v132, v131, v130
	v_cmp_ge_f32_e64 s[0:1], 0, v133
	v_add_u32_e32 v133, 1, v131
	s_nop 0
	v_cndmask_b32_e64 v132, v131, v132, s[0:1]
	v_fma_f32 v131, -v133, v131, v130
	v_cmp_lt_f32_e64 s[0:1], 0, v131
	s_nop 1
	v_cndmask_b32_e64 v131, v132, v133, s[0:1]
	v_mul_f32_e32 v132, 0x37800000, v131
	v_cndmask_b32_e32 v131, v131, v132, vcc
	v_cmp_class_f32_e32 vcc, v130, v226
	s_nop 1
	v_cndmask_b32_e32 v130, v131, v130, vcc
	v_div_scale_f32 v131, s[0:1], v130, v130, 1.0
	v_rcp_f32_e32 v132, v131
	s_nop 0
	v_fma_f32 v133, -v131, v132, 1.0
	v_fmac_f32_e32 v132, v133, v132
	v_div_scale_f32 v133, vcc, 1.0, v130, 1.0
	v_mul_f32_e32 v134, v133, v132
	v_fma_f32 v135, -v131, v134, v133
	v_fmac_f32_e32 v134, v135, v132
	v_fma_f32 v131, -v131, v134, v133
	v_div_fmas_f32 v131, v131, v132, v134
	v_div_fixup_f32 v208, v131, v130, 1.0
	v_lshl_add_u64 v[130:131], v[202:203], 2, s[34:35]
	global_load_dword v130, v[130:131], off
	s_waitcnt vmcnt(0)
	v_fmamk_f32 v130, v130, 0x3a000000, v225
	v_cmp_gt_f32_e32 vcc, s84, v130
	v_mul_f32_e32 v131, 0x4f800000, v130
	s_nop 0
	v_cndmask_b32_e32 v130, v130, v131, vcc
	v_sqrt_f32_e32 v131, v130
	s_nop 0
	v_add_u32_e32 v132, -1, v131
	v_fma_f32 v133, -v132, v131, v130
	v_cmp_ge_f32_e64 s[0:1], 0, v133
	v_add_u32_e32 v133, 1, v131
	s_nop 0
	v_cndmask_b32_e64 v132, v131, v132, s[0:1]
	v_fma_f32 v131, -v133, v131, v130
	v_cmp_lt_f32_e64 s[0:1], 0, v131
	s_nop 1
	v_cndmask_b32_e64 v131, v132, v133, s[0:1]
	v_mul_f32_e32 v132, 0x37800000, v131
	v_cndmask_b32_e32 v131, v131, v132, vcc
	v_cmp_class_f32_e32 vcc, v130, v226
	s_nop 1
	v_cndmask_b32_e32 v130, v131, v130, vcc
	v_div_scale_f32 v131, s[0:1], v130, v130, 1.0
	v_rcp_f32_e32 v132, v131
	s_nop 0
	v_fma_f32 v133, -v131, v132, 1.0
	v_fmac_f32_e32 v132, v133, v132
	v_div_scale_f32 v133, vcc, 1.0, v130, 1.0
	v_mul_f32_e32 v134, v133, v132
	v_fma_f32 v135, -v131, v134, v133
	v_fmac_f32_e32 v134, v135, v132
	v_fma_f32 v131, -v131, v134, v133
	v_div_fmas_f32 v131, v131, v132, v134
	v_div_fixup_f32 v198, v131, v130, 1.0
	v_lshl_add_u64 v[130:131], v[204:205], 2, s[34:35]
	global_load_dword v130, v[130:131], off
	s_waitcnt vmcnt(0)
	v_fmamk_f32 v130, v130, 0x3a000000, v225
	v_cmp_gt_f32_e32 vcc, s84, v130
	v_mul_f32_e32 v131, 0x4f800000, v130
	s_nop 0
	v_cndmask_b32_e32 v130, v130, v131, vcc
	v_sqrt_f32_e32 v131, v130
	s_nop 0
	v_add_u32_e32 v132, -1, v131
	v_fma_f32 v133, -v132, v131, v130
	v_cmp_ge_f32_e64 s[0:1], 0, v133
	v_add_u32_e32 v133, 1, v131
	s_nop 0
	v_cndmask_b32_e64 v132, v131, v132, s[0:1]
	v_fma_f32 v131, -v133, v131, v130
	v_cmp_lt_f32_e64 s[0:1], 0, v131
	s_nop 1
	v_cndmask_b32_e64 v131, v132, v133, s[0:1]
	v_mul_f32_e32 v132, 0x37800000, v131
	v_cndmask_b32_e32 v131, v131, v132, vcc
	v_cmp_class_f32_e32 vcc, v130, v226
	s_nop 1
	v_cndmask_b32_e32 v130, v131, v130, vcc
	v_div_scale_f32 v131, s[0:1], v130, v130, 1.0
	v_rcp_f32_e32 v132, v131
	s_nop 0
	v_fma_f32 v133, -v131, v132, 1.0
	v_fmac_f32_e32 v132, v133, v132
	v_div_scale_f32 v133, vcc, 1.0, v130, 1.0
	v_mul_f32_e32 v134, v133, v132
	v_fma_f32 v135, -v131, v134, v133
	v_fmac_f32_e32 v134, v135, v132
	v_fma_f32 v131, -v131, v134, v133
	v_div_fmas_f32 v131, v131, v132, v134
	v_div_fixup_f32 v200, v131, v130, 1.0
	global_load_dword v130, v[128:129], off offset:512
	s_waitcnt vmcnt(0)
	v_fmamk_f32 v130, v130, 0x3a000000, v225
	v_cmp_gt_f32_e32 vcc, s84, v130
	v_mul_f32_e32 v131, 0x4f800000, v130
	s_nop 0
	v_cndmask_b32_e32 v130, v130, v131, vcc
	v_sqrt_f32_e32 v131, v130
	s_nop 0
	v_add_u32_e32 v132, -1, v131
	v_fma_f32 v133, -v132, v131, v130
	v_cmp_ge_f32_e64 s[0:1], 0, v133
	v_add_u32_e32 v133, 1, v131
	s_nop 0
	v_cndmask_b32_e64 v132, v131, v132, s[0:1]
	v_fma_f32 v131, -v133, v131, v130
	v_cmp_lt_f32_e64 s[0:1], 0, v131
	s_nop 1
	v_cndmask_b32_e64 v131, v132, v133, s[0:1]
	v_mul_f32_e32 v132, 0x37800000, v131
	v_cndmask_b32_e32 v131, v131, v132, vcc
	v_cmp_class_f32_e32 vcc, v130, v226
	s_nop 1
	v_cndmask_b32_e32 v130, v131, v130, vcc
	v_div_scale_f32 v131, s[0:1], v130, v130, 1.0
	v_rcp_f32_e32 v132, v131
	s_nop 0
	v_fma_f32 v133, -v131, v132, 1.0
	v_fmac_f32_e32 v132, v133, v132
	v_div_scale_f32 v133, vcc, 1.0, v130, 1.0
	v_mul_f32_e32 v134, v133, v132
	v_fma_f32 v135, -v131, v134, v133
	v_fmac_f32_e32 v134, v135, v132
	v_fma_f32 v131, -v131, v134, v133
	v_div_fmas_f32 v131, v131, v132, v134
	v_div_fixup_f32 v194, v131, v130, 1.0
	global_load_dword v130, v[128:129], off offset:576
	s_waitcnt vmcnt(0)
	v_fmamk_f32 v130, v130, 0x3a000000, v225
	v_cmp_gt_f32_e32 vcc, s84, v130
	v_mul_f32_e32 v131, 0x4f800000, v130
	s_nop 0
	v_cndmask_b32_e32 v130, v130, v131, vcc
	v_sqrt_f32_e32 v131, v130
	s_nop 0
	v_add_u32_e32 v132, -1, v131
	v_fma_f32 v133, -v132, v131, v130
	v_cmp_ge_f32_e64 s[0:1], 0, v133
	v_add_u32_e32 v133, 1, v131
	s_nop 0
	v_cndmask_b32_e64 v132, v131, v132, s[0:1]
	v_fma_f32 v131, -v133, v131, v130
	v_cmp_lt_f32_e64 s[0:1], 0, v131
	s_nop 1
	v_cndmask_b32_e64 v131, v132, v133, s[0:1]
	v_mul_f32_e32 v132, 0x37800000, v131
	v_cndmask_b32_e32 v131, v131, v132, vcc
	v_cmp_class_f32_e32 vcc, v130, v226
	s_nop 1
	v_cndmask_b32_e32 v130, v131, v130, vcc
	v_div_scale_f32 v131, s[0:1], v130, v130, 1.0
	v_rcp_f32_e32 v132, v131
	s_nop 0
	v_fma_f32 v133, -v131, v132, 1.0
	v_fmac_f32_e32 v132, v133, v132
	v_div_scale_f32 v133, vcc, 1.0, v130, 1.0
	v_mul_f32_e32 v134, v133, v132
	v_fma_f32 v135, -v131, v134, v133
	v_fmac_f32_e32 v134, v135, v132
	v_fma_f32 v131, -v131, v134, v133
	v_div_fmas_f32 v131, v131, v132, v134
	v_div_fixup_f32 v196, v131, v130, 1.0
	global_load_dword v130, v[128:129], off offset:640
	s_waitcnt vmcnt(0)
	v_fmamk_f32 v130, v130, 0x3a000000, v225
	global_load_dword v128, v[128:129], off offset:704
	v_cmp_gt_f32_e32 vcc, s84, v130
	v_mul_f32_e32 v131, 0x4f800000, v130
	s_waitcnt vmcnt(0)
	v_fmamk_f32 v128, v128, 0x3a000000, v225
	v_cndmask_b32_e32 v130, v130, v131, vcc
	v_sqrt_f32_e32 v131, v130
	v_mul_f32_e32 v129, 0x4f800000, v128
	v_add_u32_e32 v132, -1, v131
	v_fma_f32 v133, -v132, v131, v130
	v_cmp_ge_f32_e64 s[0:1], 0, v133
	v_add_u32_e32 v133, 1, v131
	s_nop 0
	v_cndmask_b32_e64 v132, v131, v132, s[0:1]
	v_fma_f32 v131, -v133, v131, v130
	v_cmp_lt_f32_e64 s[0:1], 0, v131
	s_nop 1
	v_cndmask_b32_e64 v131, v132, v133, s[0:1]
	v_mul_f32_e32 v132, 0x37800000, v131
	v_cndmask_b32_e32 v131, v131, v132, vcc
	v_cmp_class_f32_e32 vcc, v130, v226
	s_nop 1
	v_cndmask_b32_e32 v130, v131, v130, vcc
	v_div_scale_f32 v131, s[0:1], v130, v130, 1.0
	v_rcp_f32_e32 v132, v131
	s_nop 0
	v_fma_f32 v133, -v131, v132, 1.0
	v_fmac_f32_e32 v132, v133, v132
	v_div_scale_f32 v133, vcc, 1.0, v130, 1.0
	v_mul_f32_e32 v134, v133, v132
	v_fma_f32 v135, -v131, v134, v133
	v_fmac_f32_e32 v134, v135, v132
	v_fma_f32 v131, -v131, v134, v133
	v_div_fmas_f32 v131, v131, v132, v134
	v_cmp_gt_f32_e32 vcc, s84, v128
	v_div_fixup_f32 v192, v131, v130, 1.0
	s_nop 0
	v_cndmask_b32_e32 v128, v128, v129, vcc
	v_sqrt_f32_e32 v129, v128
	s_nop 0
	v_add_u32_e32 v130, -1, v129
	v_fma_f32 v131, -v130, v129, v128
	v_cmp_ge_f32_e64 s[0:1], 0, v131
	v_add_u32_e32 v131, 1, v129
	s_nop 0
	v_cndmask_b32_e64 v130, v129, v130, s[0:1]
	v_fma_f32 v129, -v131, v129, v128
	v_cmp_lt_f32_e64 s[0:1], 0, v129
	s_nop 1
	v_cndmask_b32_e64 v129, v130, v131, s[0:1]
	v_mul_f32_e32 v130, 0x37800000, v129
	v_cndmask_b32_e32 v129, v129, v130, vcc
	v_cmp_class_f32_e32 vcc, v128, v226
	s_nop 1
	v_cndmask_b32_e32 v128, v129, v128, vcc
	v_div_scale_f32 v129, s[0:1], v128, v128, 1.0
	v_rcp_f32_e32 v130, v129
	s_mov_b64 s[0:1], -1
	v_fma_f32 v131, -v129, v130, 1.0
	v_fmac_f32_e32 v130, v131, v130
	v_div_scale_f32 v131, vcc, 1.0, v128, 1.0
	v_mul_f32_e32 v132, v131, v130
	v_fma_f32 v133, -v129, v132, v131
	v_fmac_f32_e32 v132, v133, v130
	v_fma_f32 v129, -v129, v132, v131
	v_div_fmas_f32 v129, v129, v130, v132
	v_div_fixup_f32 v214, v129, v128, 1.0
	v_and_b32_e32 v130, 15, v220
	v_lshrrev_b32_e32 v131, 6, v220
	v_lshlrev_b32_e32 v130, 5, v130
	v_lshl_add_u32 v130, v131, 9, v130
	v_add_u32_e32 v130, 0x20000, v130
	v_mov_b32_e32 v132, v206
	v_mov_b32_e32 v133, v208
	v_mov_b32_e32 v134, v198
	v_mov_b32_e32 v135, v200
	ds_write_b128 v130, v[132:135]
	s_waitcnt lgkmcnt(0)
	v_mov_b32_e32 v132, v194
	v_mov_b32_e32 v133, v196
	v_mov_b32_e32 v134, v192
	v_mov_b32_e32 v135, v214
	ds_write_b128 v130, v[132:135] offset:16
	s_mov_b32 s98, s12
.Lrstd_join_326:
	s_cbranch_scc1 .LBB0_329
	s_andn2_b64 vcc, exec, s[0:1]
	s_cbranch_vccz .LBB0_414
